# G1 K-loop: hoisted compiler's stray s_waitcnt vmcnt(0) from loop head to preheader
# baseline (speedup 1.0000x reference)
; #define PG8_STAGE(bufoff, gbase, voff) do { _Pragma("unroll") for (int _i = 0; _i < 2; ++_i) \
;         __builtin_amdgcn_global_load_lds((const unsigned*)((const char*)(gbase) + (voff)[_i]), (LAS unsigned*)(lds + (bufoff) + ldsw + _i * 8192), 16, 0, 0); } while (0)
; #define PG8_LDA(dst, b, h) do { _Pragma("unroll") for (int m = 0; m < 4; ++m) _Pragma("unroll") for (int k = 0; k < 2; ++k) dst[m][k] = *(const LAS bf16x8*)(lds + PG8_SA(b, h) + aoff + m * 2048 + k * 1024); } while (0)
; #define PG8_LDB(dst, b, h) do { _Pragma("unroll") for (int n = 0; n < 2; ++n) _Pragma("unroll") for (int k = 0; k < 2; ++k) dst[n][k] = *(const LAS bf16x8*)(lds + PG8_SB(b, h) + boff + n * 2048 + k * 1024); } while (0)
; #define PG8_MMA(ai, bj, At, Bt) do { __builtin_amdgcn_s_setprio(1); _Pragma("unroll") for (int m = 0; m < 4; ++m) _Pragma("unroll") for (int n = 0; n < 2; ++n) _Pragma("unroll") for (int k = 0; k < 2; ++k) \
;         acc[ai][bj][m][n] = __builtin_amdgcn_mfma_f32_16x16x32_bf16(Bt[n][k], At[m][k], acc[ai][bj][m][n], 0, 0, 0); __builtin_amdgcn_s_setprio(0); } while (0)
; #define PG8_WAIT_V(n) asm volatile("s_waitcnt vmcnt(" #n ")" ::: "memory")
; #define PG8_WAIT_L(n) asm volatile("s_waitcnt lgkmcnt(" #n ")" ::: "memory")
; #define PG8_BAR __builtin_amdgcn_s_barrier()
; #define PG8_SCHED __builtin_amdgcn_sched_barrier(0)
; template <class Epi, class Sched>
; __device__ __forceinline__ void gemm_phase(LAS unsigned char* lds, const int lda, const int ldb, const Sched& S, const Epi& E) {
;     ...
;         for (int t = 0; t < nt; t += 2) {
;             const bool last = (t == nt - 2);
;             const char* a1 = cA + (size_t)(t + 1) * kstep;
;             const char* a2 = last ? nA : cA + (size_t)(t + 2) * kstep; const char* b2 = last ? nB : cB + (size_t)(t + 2) * kstep;
;             const char* a3 = a2 + kstep; const char* b3 = b2 + kstep;
;             PG8_LDB(B0, 0, 0); PG8_LDB(B1, 0, 1); PG8_SCHED; PG8_LDA(At, 0, 0); PG8_STAGE(PG8_SA(1, 1), a1 + hstepA, voffA);
;             PG8_WAIT_V(8); PG8_WAIT_L(0); PG8_BAR; PG8_MMA(0, 0, At, B0); PG8_MMA(0, 1, At, B1); PG8_BAR; PG8_SCHED;
;     ...
;         for (int a = 0; a < 2; ++a)
; #pragma unroll
;             for (int b = 0; b < 2; ++b)
; #pragma unroll
;                 for (int m = 0; m < 4; ++m)
; #pragma unroll
;                     for (int n = 0; n < 2; ++n) acc[a][b][m][n] = (f32x4){0.f, 0.f, 0.f, 0.f};
.LBB0_192:
	s_add_u32 s35, s50, 0x100
	s_addc_u32 s52, s51, 0
	s_add_u32 s42, s48, 0x80080
	v_mov_b32_e32 v2, 0
	s_addc_u32 s43, s49, 0
	s_mov_b32 s53, -2
	v_mov_b32_e32 v3, v2
	v_mov_b32_e32 v4, v2
	v_mov_b32_e32 v5, v2
	v_mov_b32_e32 v6, v2
	v_mov_b32_e32 v7, v2
	v_mov_b32_e32 v8, v2
	v_mov_b32_e32 v9, v2
	v_mov_b32_e32 v18, v2
	v_mov_b32_e32 v19, v2
	v_mov_b32_e32 v20, v2
	v_mov_b32_e32 v21, v2
	v_mov_b32_e32 v22, v2
	v_mov_b32_e32 v23, v2
	v_mov_b32_e32 v24, v2
	v_mov_b32_e32 v25, v2
	v_mov_b32_e32 v34, v2
	v_mov_b32_e32 v35, v2
	v_mov_b32_e32 v36, v2
	v_mov_b32_e32 v37, v2
	v_mov_b32_e32 v38, v2
	v_mov_b32_e32 v39, v2
	v_mov_b32_e32 v40, v2
	v_mov_b32_e32 v41, v2
	v_mov_b32_e32 v66, v2
	v_mov_b32_e32 v67, v2
	v_mov_b32_e32 v68, v2
	v_mov_b32_e32 v69, v2
	v_mov_b32_e32 v70, v2
	v_mov_b32_e32 v71, v2
	v_mov_b32_e32 v72, v2
	v_mov_b32_e32 v73, v2
	v_mov_b32_e32 v10, v2
	v_mov_b32_e32 v11, v2
	v_mov_b32_e32 v12, v2
	v_mov_b32_e32 v13, v2
	v_mov_b32_e32 v14, v2
	v_mov_b32_e32 v15, v2
	v_mov_b32_e32 v16, v2
	v_mov_b32_e32 v17, v2
	v_mov_b32_e32 v26, v2
	v_mov_b32_e32 v27, v2
	v_mov_b32_e32 v28, v2
	v_mov_b32_e32 v29, v2
	v_mov_b32_e32 v30, v2
	v_mov_b32_e32 v31, v2
	v_mov_b32_e32 v32, v2
	v_mov_b32_e32 v33, v2
	v_mov_b32_e32 v50, v2
	v_mov_b32_e32 v51, v2
	v_mov_b32_e32 v52, v2
	v_mov_b32_e32 v53, v2
	v_mov_b32_e32 v54, v2
	v_mov_b32_e32 v55, v2
	v_mov_b32_e32 v56, v2
	v_mov_b32_e32 v57, v2
	v_mov_b32_e32 v74, v2
	v_mov_b32_e32 v75, v2
	v_mov_b32_e32 v76, v2
	v_mov_b32_e32 v77, v2
	v_mov_b32_e32 v78, v2
	v_mov_b32_e32 v79, v2
	v_mov_b32_e32 v80, v2
	v_mov_b32_e32 v81, v2
	v_mov_b32_e32 v82, v2
	v_mov_b32_e32 v83, v2
	v_mov_b32_e32 v84, v2
	v_mov_b32_e32 v85, v2
	v_mov_b32_e32 v86, v2
	v_mov_b32_e32 v87, v2
	v_mov_b32_e32 v88, v2
	v_mov_b32_e32 v89, v2
	v_mov_b32_e32 v98, v2
	v_mov_b32_e32 v99, v2
	v_mov_b32_e32 v100, v2
	v_mov_b32_e32 v101, v2
	v_mov_b32_e32 v102, v2
	v_mov_b32_e32 v103, v2
	v_mov_b32_e32 v104, v2
	v_mov_b32_e32 v105, v2
	v_mov_b32_e32 v114, v2
	v_mov_b32_e32 v115, v2
	v_mov_b32_e32 v116, v2
	v_mov_b32_e32 v117, v2
	v_mov_b32_e32 v118, v2
	v_mov_b32_e32 v119, v2
	v_mov_b32_e32 v120, v2
	v_mov_b32_e32 v121, v2
	v_mov_b32_e32 v130, v2
	v_mov_b32_e32 v131, v2
	v_mov_b32_e32 v132, v2
	v_mov_b32_e32 v133, v2
	v_mov_b32_e32 v134, v2
	v_mov_b32_e32 v135, v2
	v_mov_b32_e32 v136, v2
	v_mov_b32_e32 v137, v2
	v_mov_b32_e32 v90, v2
	v_mov_b32_e32 v91, v2
	v_mov_b32_e32 v92, v2
	v_mov_b32_e32 v93, v2
	v_mov_b32_e32 v94, v2
	v_mov_b32_e32 v95, v2
	v_mov_b32_e32 v96, v2
	v_mov_b32_e32 v97, v2
	v_mov_b32_e32 v106, v2
	v_mov_b32_e32 v107, v2
	v_mov_b32_e32 v108, v2
	v_mov_b32_e32 v109, v2
	v_mov_b32_e32 v110, v2
	v_mov_b32_e32 v111, v2
	v_mov_b32_e32 v112, v2
	v_mov_b32_e32 v113, v2
	v_mov_b32_e32 v122, v2
	v_mov_b32_e32 v123, v2
	v_mov_b32_e32 v124, v2
	v_mov_b32_e32 v125, v2
	v_mov_b32_e32 v126, v2
	v_mov_b32_e32 v127, v2
	v_mov_b32_e32 v128, v2
	v_mov_b32_e32 v129, v2
	v_mov_b32_e32 v138, v2
	v_mov_b32_e32 v139, v2
	v_mov_b32_e32 v140, v2
	v_mov_b32_e32 v141, v2
	v_mov_b32_e32 v142, v2
	v_mov_b32_e32 v143, v2
	v_mov_b32_e32 v144, v2
	v_mov_b32_e32 v145, v2
	s_waitcnt vmcnt(0)
.LBB0_193:
	s_add_u32 s48, s42, 0xfff80080
	s_addc_u32 s49, s43, -1
	s_add_i32 s66, 0, 0x10000
	s_cmp_eq_u32 s53, 28
	s_cselect_b32 s51, s41, s49
	s_cselect_b32 s50, s40, s48
	v_add_u32_e32 v0, s66, v165
	s_cselect_b32 s49, s47, s52
	s_cselect_b32 s48, s46, s35
	s_add_i32 s89, 0, 0x14000
	ds_read_b128 v[42:45], v0
	ds_read_b128 v[46:49], v0 offset:1024
	ds_read_b128 v[58:61], v0 offset:2048
	ds_read_b128 v[62:65], v0 offset:3072
	v_add_u32_e32 v0, s89, v165
	ds_read_b128 v[158:161], v0
	ds_read_b128 v[166:169], v0 offset:1024
	ds_read_b128 v[172:175], v0 offset:2048
	ds_read_b128 v[176:179], v0 offset:3072
	v_lshl_add_u64 v[228:229], s[42:43], 0, v[156:157]
	s_add_i32 m0, s59, 0xc000
	ds_read_b128 v[180:183], v170
	ds_read_b128 v[184:187], v170 offset:1024
	ds_read_b128 v[188:191], v170 offset:2048
	ds_read_b128 v[192:195], v170 offset:3072
	ds_read_b128 v[196:199], v170 offset:4096
	ds_read_b128 v[200:203], v170 offset:5120
	ds_read_b128 v[204:207], v170 offset:6144
	ds_read_b128 v[224:227], v170 offset:7168
	global_load_lds_dwordx4 v[228:229], off
	v_lshl_add_u64 v[228:229], s[42:43], 0, v[154:155]
	s_add_i32 m0, s59, 0xe000
	s_nop 0
	global_load_lds_dwordx4 v[228:229], off
	s_waitcnt vmcnt(8)
	s_waitcnt lgkmcnt(0)
	s_barrier
	s_setprio 1
	s_waitcnt lgkmcnt(0)
	v_mfma_f32_16x16x32_bf16 v[142:145], v[42:45], v[180:183], v[142:145]
	v_mfma_f32_16x16x32_bf16 v[138:141], v[58:61], v[180:183], v[138:141]
	v_mfma_f32_16x16x32_bf16 v[126:129], v[42:45], v[188:191], v[126:129]
	v_mfma_f32_16x16x32_bf16 v[122:125], v[58:61], v[188:191], v[122:125]
	v_mfma_f32_16x16x32_bf16 v[110:113], v[42:45], v[196:199], v[110:113]
	v_mfma_f32_16x16x32_bf16 v[106:109], v[58:61], v[196:199], v[106:109]
	v_mfma_f32_16x16x32_bf16 v[94:97], v[42:45], v[204:207], v[94:97]
	v_mfma_f32_16x16x32_bf16 v[90:93], v[58:61], v[204:207], v[90:93]
	v_mfma_f32_16x16x32_bf16 v[142:145], v[46:49], v[184:187], v[142:145]
	v_mfma_f32_16x16x32_bf16 v[138:141], v[62:65], v[184:187], v[138:141]
	v_mfma_f32_16x16x32_bf16 v[126:129], v[46:49], v[192:195], v[126:129]
	v_mfma_f32_16x16x32_bf16 v[122:125], v[62:65], v[192:195], v[122:125]
	v_mfma_f32_16x16x32_bf16 v[110:113], v[46:49], v[200:203], v[110:113]
	v_mfma_f32_16x16x32_bf16 v[106:109], v[62:65], v[200:203], v[106:109]
	v_mfma_f32_16x16x32_bf16 v[94:97], v[46:49], v[224:227], v[94:97]
	v_mfma_f32_16x16x32_bf16 v[90:93], v[62:65], v[224:227], v[90:93]
	s_setprio 0
	s_setprio 1
	v_mfma_f32_16x16x32_bf16 v[134:137], v[158:161], v[180:183], v[134:137]
	v_mfma_f32_16x16x32_bf16 v[130:133], v[172:175], v[180:183], v[130:133]
	v_mfma_f32_16x16x32_bf16 v[118:121], v[158:161], v[188:191], v[118:121]
	v_mfma_f32_16x16x32_bf16 v[114:117], v[172:175], v[188:191], v[114:117]
	v_mfma_f32_16x16x32_bf16 v[102:105], v[158:161], v[196:199], v[102:105]
	v_mfma_f32_16x16x32_bf16 v[98:101], v[172:175], v[196:199], v[98:101]
	v_mfma_f32_16x16x32_bf16 v[86:89], v[158:161], v[204:207], v[86:89]
	v_mfma_f32_16x16x32_bf16 v[82:85], v[172:175], v[204:207], v[82:85]
	v_mfma_f32_16x16x32_bf16 v[134:137], v[166:169], v[184:187], v[134:137]
	v_mfma_f32_16x16x32_bf16 v[130:133], v[176:179], v[184:187], v[130:133]
	v_mfma_f32_16x16x32_bf16 v[118:121], v[166:169], v[192:195], v[118:121]
	v_mfma_f32_16x16x32_bf16 v[114:117], v[176:179], v[192:195], v[114:117]
	v_mfma_f32_16x16x32_bf16 v[102:105], v[166:169], v[200:203], v[102:105]
	v_mfma_f32_16x16x32_bf16 v[98:101], v[176:179], v[200:203], v[98:101]
	v_mfma_f32_16x16x32_bf16 v[86:89], v[166:169], v[224:227], v[86:89]
	v_mfma_f32_16x16x32_bf16 v[82:85], v[176:179], v[224:227], v[82:85]
	s_setprio 0
	s_barrier
; #define PG8_STAGE(bufoff, gbase, voff) do { _Pragma("unroll") for (int _i = 0; _i < 2; ++_i) \
;         __builtin_amdgcn_global_load_lds((const unsigned*)((const char*)(gbase) + (voff)[_i]), (LAS unsigned*)(lds + (bufoff) + ldsw + _i * 8192), 16, 0, 0); } while (0)
; #define PG8_LDA(dst, b, h) do { _Pragma("unroll") for (int m = 0; m < 4; ++m) _Pragma("unroll") for (int k = 0; k < 2; ++k) dst[m][k] = *(const LAS bf16x8*)(lds + PG8_SA(b, h) + aoff + m * 2048 + k * 1024); } while (0)
; #define PG8_LDB(dst, b, h) do { _Pragma("unroll") for (int n = 0; n < 2; ++n) _Pragma("unroll") for (int k = 0; k < 2; ++k) dst[n][k] = *(const LAS bf16x8*)(lds + PG8_SB(b, h) + boff + n * 2048 + k * 1024); } while (0)
; #define PG8_MMA(ai, bj, At, Bt) do { __builtin_amdgcn_s_setprio(1); _Pragma("unroll") for (int m = 0; m < 4; ++m) _Pragma("unroll") for (int n = 0; n < 2; ++n) _Pragma("unroll") for (int k = 0; k < 2; ++k) \
;         acc[ai][bj][m][n] = __builtin_amdgcn_mfma_f32_16x16x32_bf16(Bt[n][k], At[m][k], acc[ai][bj][m][n], 0, 0, 0); __builtin_amdgcn_s_setprio(0); } while (0)
; #define PG8_WAIT_V(n) asm volatile("s_waitcnt vmcnt(" #n ")" ::: "memory")
; #define PG8_WAIT_L(n) asm volatile("s_waitcnt lgkmcnt(" #n ")" ::: "memory")
; #define PG8_BAR __builtin_amdgcn_s_barrier()
; #define PG8_SCHED __builtin_amdgcn_sched_barrier(0)
; template <class Epi, class Sched>
; __device__ __forceinline__ void gemm_phase(LAS unsigned char* lds, const int lda, const int ldb, const Sched& S, const Epi& E) {
;     ...
;             PG8_LDA(At, 0, 1); PG8_STAGE(PG8_SB(0, 0), b2, voffB); PG8_STAGE(PG8_SB(0, 1), b2 + hstepB, voffB); PG8_STAGE(PG8_SA(0, 0), a2, voffA);
;             PG8_WAIT_V(8); PG8_WAIT_L(0); PG8_BAR; PG8_MMA(1, 0, At, B0); PG8_MMA(1, 1, At, B1); PG8_BAR; PG8_SCHED;
;             PG8_LDB(B0, 1, 0); PG8_LDB(B1, 1, 1); PG8_SCHED; PG8_LDA(At, 1, 0); PG8_STAGE(PG8_SA(0, 1), a2 + hstepA, voffA);
;             PG8_WAIT_V(8); PG8_WAIT_L(0); PG8_BAR; PG8_MMA(0, 0, At, B0); PG8_MMA(0, 1, At, B1); PG8_BAR; PG8_SCHED;
	s_add_i32 s66, s66, s58
	v_lshl_add_u64 v[228:229], s[48:49], 0, v[148:149]
	s_mov_b32 m0, s66
	ds_read_b128 v[180:183], v170 offset:16384
	ds_read_b128 v[184:187], v170 offset:17408
	ds_read_b128 v[188:191], v170 offset:18432
	ds_read_b128 v[192:195], v170 offset:19456
	ds_read_b128 v[196:199], v170 offset:20480
	ds_read_b128 v[200:203], v170 offset:21504
	ds_read_b128 v[204:207], v170 offset:22528
	ds_read_b128 v[224:227], v170 offset:23552
	global_load_lds_dwordx4 v[228:229], off
	s_add_i32 m0, s66, 0x2000
	s_add_u32 s66, s48, 0x80000
	v_lshl_add_u64 v[230:231], s[48:49], 0, v[152:153]
	s_addc_u32 s67, s49, 0
	s_add_i32 s89, s89, s58
	global_load_lds_dwordx4 v[230:231], off
	v_lshl_add_u64 v[232:233], s[66:67], 0, v[148:149]
	s_mov_b32 m0, s89
	v_lshl_add_u64 v[234:235], s[50:51], 0, v[150:151]
	global_load_lds_dwordx4 v[232:233], off
	v_lshl_add_u64 v[232:233], s[66:67], 0, v[152:153]
	s_add_i32 m0, s89, 0x2000
	s_nop 0
	global_load_lds_dwordx4 v[232:233], off
	v_lshl_add_u64 v[232:233], s[50:51], 0, v[146:147]
	s_mov_b32 m0, s59
	s_nop 0
	global_load_lds_dwordx4 v[232:233], off
	s_mov_b32 m0, s60
	s_nop 0
	global_load_lds_dwordx4 v[234:235], off
	s_waitcnt vmcnt(8)
	s_waitcnt lgkmcnt(0)
	s_barrier
	s_setprio 1
	s_waitcnt lgkmcnt(0)
	v_mfma_f32_16x16x32_bf16 v[78:81], v[42:45], v[180:183], v[78:81]
	v_mfma_f32_16x16x32_bf16 v[74:77], v[58:61], v[180:183], v[74:77]
	v_mfma_f32_16x16x32_bf16 v[54:57], v[42:45], v[188:191], v[54:57]
	v_mfma_f32_16x16x32_bf16 v[50:53], v[58:61], v[188:191], v[50:53]
	v_mfma_f32_16x16x32_bf16 v[30:33], v[42:45], v[196:199], v[30:33]
	v_mfma_f32_16x16x32_bf16 v[26:29], v[58:61], v[196:199], v[26:29]
	v_mfma_f32_16x16x32_bf16 v[14:17], v[42:45], v[204:207], v[14:17]
	v_mfma_f32_16x16x32_bf16 v[10:13], v[58:61], v[204:207], v[10:13]
	v_mfma_f32_16x16x32_bf16 v[78:81], v[46:49], v[184:187], v[78:81]
	v_mfma_f32_16x16x32_bf16 v[74:77], v[62:65], v[184:187], v[74:77]
	v_mfma_f32_16x16x32_bf16 v[54:57], v[46:49], v[192:195], v[54:57]
	v_mfma_f32_16x16x32_bf16 v[50:53], v[62:65], v[192:195], v[50:53]
	v_mfma_f32_16x16x32_bf16 v[30:33], v[46:49], v[200:203], v[30:33]
	v_mfma_f32_16x16x32_bf16 v[26:29], v[62:65], v[200:203], v[26:29]
	v_mfma_f32_16x16x32_bf16 v[14:17], v[46:49], v[224:227], v[14:17]
	v_mfma_f32_16x16x32_bf16 v[10:13], v[62:65], v[224:227], v[10:13]
	s_setprio 0
	s_setprio 1
	v_mfma_f32_16x16x32_bf16 v[38:41], v[158:161], v[188:191], v[38:41]
	v_mfma_f32_16x16x32_bf16 v[34:37], v[172:175], v[188:191], v[34:37]
	v_mfma_f32_16x16x32_bf16 v[22:25], v[158:161], v[196:199], v[22:25]
	v_mfma_f32_16x16x32_bf16 v[18:21], v[172:175], v[196:199], v[18:21]
	v_mfma_f32_16x16x32_bf16 v[6:9], v[158:161], v[204:207], v[6:9]
	v_mfma_f32_16x16x32_bf16 v[2:5], v[172:175], v[204:207], v[2:5]
	v_mfma_f32_16x16x32_bf16 v[42:45], v[158:161], v[180:183], v[70:73]
	v_mfma_f32_16x16x32_bf16 v[46:49], v[172:175], v[180:183], v[66:69]
	v_mfma_f32_16x16x32_bf16 v[38:41], v[166:169], v[192:195], v[38:41]
	v_mfma_f32_16x16x32_bf16 v[34:37], v[176:179], v[192:195], v[34:37]
	v_mfma_f32_16x16x32_bf16 v[22:25], v[166:169], v[200:203], v[22:25]
	v_mfma_f32_16x16x32_bf16 v[18:21], v[176:179], v[200:203], v[18:21]
	v_mfma_f32_16x16x32_bf16 v[6:9], v[166:169], v[224:227], v[6:9]
	v_mfma_f32_16x16x32_bf16 v[2:5], v[176:179], v[224:227], v[2:5]
	v_mfma_f32_16x16x32_bf16 v[42:45], v[166:169], v[184:187], v[42:45]
	v_mfma_f32_16x16x32_bf16 v[46:49], v[176:179], v[184:187], v[46:49]
	s_setprio 0
	s_barrier
	s_add_i32 s66, 0, 0x18000
	v_add_u32_e32 v0, s66, v165
	s_add_i32 s67, 0, 0x1c000
	ds_read_b128 v[58:61], v0
	ds_read_b128 v[62:65], v0 offset:1024
	ds_read_b128 v[66:69], v0 offset:2048
	ds_read_b128 v[70:73], v0 offset:3072
	v_add_u32_e32 v0, s67, v165
	ds_read_b128 v[158:161], v0
	ds_read_b128 v[166:169], v0 offset:1024
	ds_read_b128 v[172:175], v0 offset:2048
	ds_read_b128 v[176:179], v0 offset:3072
	s_add_u32 s50, s50, 0x80000
	s_addc_u32 s51, s51, 0
	s_mov_b32 m0, s61
	v_lshl_add_u64 v[236:237], s[50:51], 0, v[146:147]
	ds_read_b128 v[180:183], v170 offset:32768
	ds_read_b128 v[184:187], v170 offset:33792
	ds_read_b128 v[188:191], v170 offset:34816
	ds_read_b128 v[192:195], v170 offset:35840
	ds_read_b128 v[196:199], v170 offset:36864
	ds_read_b128 v[200:203], v170 offset:37888
	ds_read_b128 v[204:207], v170 offset:38912
	ds_read_b128 v[224:227], v170 offset:39936
	global_load_lds_dwordx4 v[236:237], off
	v_lshl_add_u64 v[236:237], s[50:51], 0, v[150:151]
	s_mov_b32 m0, s68
	s_nop 0
	global_load_lds_dwordx4 v[236:237], off
	s_waitcnt vmcnt(8)
	s_waitcnt lgkmcnt(0)
	s_barrier
; #define PG8_STAGE(bufoff, gbase, voff) do { _Pragma("unroll") for (int _i = 0; _i < 2; ++_i) \
;         __builtin_amdgcn_global_load_lds((const unsigned*)((const char*)(gbase) + (voff)[_i]), (LAS unsigned*)(lds + (bufoff) + ldsw + _i * 8192), 16, 0, 0); } while (0)
; #define PG8_LDA(dst, b, h) do { _Pragma("unroll") for (int m = 0; m < 4; ++m) _Pragma("unroll") for (int k = 0; k < 2; ++k) dst[m][k] = *(const LAS bf16x8*)(lds + PG8_SA(b, h) + aoff + m * 2048 + k * 1024); } while (0)
; #define PG8_MMA(ai, bj, At, Bt) do { __builtin_amdgcn_s_setprio(1); _Pragma("unroll") for (int m = 0; m < 4; ++m) _Pragma("unroll") for (int n = 0; n < 2; ++n) _Pragma("unroll") for (int k = 0; k < 2; ++k) \
;         acc[ai][bj][m][n] = __builtin_amdgcn_mfma_f32_16x16x32_bf16(Bt[n][k], At[m][k], acc[ai][bj][m][n], 0, 0, 0); __builtin_amdgcn_s_setprio(0); } while (0)
; #define PG8_WAIT_V(n) asm volatile("s_waitcnt vmcnt(" #n ")" ::: "memory")
; #define PG8_WAIT_L(n) asm volatile("s_waitcnt lgkmcnt(" #n ")" ::: "memory")
; #define PG8_BAR __builtin_amdgcn_s_barrier()
; #define PG8_SCHED __builtin_amdgcn_sched_barrier(0)
; template <class Epi, class Sched>
; __device__ __forceinline__ void gemm_phase(LAS unsigned char* lds, const int lda, const int ldb, const Sched& S, const Epi& E) {
;     ...
;             PG8_WAIT_V(8); PG8_WAIT_L(0); PG8_BAR; PG8_MMA(0, 0, At, B0); PG8_MMA(0, 1, At, B1); PG8_BAR; PG8_SCHED;
;             PG8_LDA(At, 1, 1); PG8_STAGE(PG8_SB(1, 0), b3, voffB); PG8_STAGE(PG8_SB(1, 1), b3 + hstepB, voffB); PG8_STAGE(PG8_SA(1, 0), a3, voffA);
;             PG8_WAIT_V(8); PG8_WAIT_L(0); PG8_BAR; PG8_MMA(1, 0, At, B0); PG8_MMA(1, 1, At, B1); PG8_BAR; PG8_SCHED;
;         }
;         if (wr == 0) PG8_BAR;
	s_setprio 1
	s_waitcnt lgkmcnt(0)
	v_mfma_f32_16x16x32_bf16 v[142:145], v[58:61], v[180:183], v[142:145]
	v_mfma_f32_16x16x32_bf16 v[138:141], v[66:69], v[180:183], v[138:141]
	v_mfma_f32_16x16x32_bf16 v[126:129], v[58:61], v[188:191], v[126:129]
	v_mfma_f32_16x16x32_bf16 v[122:125], v[66:69], v[188:191], v[122:125]
	v_mfma_f32_16x16x32_bf16 v[110:113], v[58:61], v[196:199], v[110:113]
	v_mfma_f32_16x16x32_bf16 v[106:109], v[66:69], v[196:199], v[106:109]
	v_mfma_f32_16x16x32_bf16 v[94:97], v[58:61], v[204:207], v[94:97]
	v_mfma_f32_16x16x32_bf16 v[90:93], v[66:69], v[204:207], v[90:93]
	v_mfma_f32_16x16x32_bf16 v[142:145], v[62:65], v[184:187], v[142:145]
	v_mfma_f32_16x16x32_bf16 v[138:141], v[70:73], v[184:187], v[138:141]
	v_mfma_f32_16x16x32_bf16 v[126:129], v[62:65], v[192:195], v[126:129]
	v_mfma_f32_16x16x32_bf16 v[122:125], v[70:73], v[192:195], v[122:125]
	v_mfma_f32_16x16x32_bf16 v[110:113], v[62:65], v[200:203], v[110:113]
	v_mfma_f32_16x16x32_bf16 v[106:109], v[70:73], v[200:203], v[106:109]
	v_mfma_f32_16x16x32_bf16 v[94:97], v[62:65], v[224:227], v[94:97]
	v_mfma_f32_16x16x32_bf16 v[90:93], v[70:73], v[224:227], v[90:93]
	s_setprio 0
	s_setprio 1
	v_mfma_f32_16x16x32_bf16 v[134:137], v[158:161], v[180:183], v[134:137]
	v_mfma_f32_16x16x32_bf16 v[130:133], v[172:175], v[180:183], v[130:133]
	v_mfma_f32_16x16x32_bf16 v[118:121], v[158:161], v[188:191], v[118:121]
	v_mfma_f32_16x16x32_bf16 v[114:117], v[172:175], v[188:191], v[114:117]
	v_mfma_f32_16x16x32_bf16 v[102:105], v[158:161], v[196:199], v[102:105]
	v_mfma_f32_16x16x32_bf16 v[98:101], v[172:175], v[196:199], v[98:101]
	v_mfma_f32_16x16x32_bf16 v[86:89], v[158:161], v[204:207], v[86:89]
	v_mfma_f32_16x16x32_bf16 v[82:85], v[172:175], v[204:207], v[82:85]
	v_mfma_f32_16x16x32_bf16 v[134:137], v[166:169], v[184:187], v[134:137]
	v_mfma_f32_16x16x32_bf16 v[130:133], v[176:179], v[184:187], v[130:133]
	v_mfma_f32_16x16x32_bf16 v[118:121], v[166:169], v[192:195], v[118:121]
	v_mfma_f32_16x16x32_bf16 v[114:117], v[176:179], v[192:195], v[114:117]
	v_mfma_f32_16x16x32_bf16 v[102:105], v[166:169], v[200:203], v[102:105]
	v_mfma_f32_16x16x32_bf16 v[98:101], v[176:179], v[200:203], v[98:101]
	v_mfma_f32_16x16x32_bf16 v[86:89], v[166:169], v[224:227], v[86:89]
	v_mfma_f32_16x16x32_bf16 v[82:85], v[176:179], v[224:227], v[82:85]
	s_setprio 0
	s_barrier
	s_add_i32 s50, s66, s58
	v_lshl_add_u64 v[228:229], v[228:229], 0, s[22:23]
	s_mov_b32 m0, s50
	ds_read_b128 v[180:183], v170 offset:49152
	ds_read_b128 v[184:187], v170 offset:50176
	ds_read_b128 v[188:191], v170 offset:51200
	ds_read_b128 v[192:195], v170 offset:52224
	ds_read_b128 v[196:199], v170 offset:53248
	ds_read_b128 v[200:203], v170 offset:54272
	ds_read_b128 v[204:207], v170 offset:55296
	ds_read_b128 v[224:227], v170 offset:56320
	global_load_lds_dwordx4 v[228:229], off
	s_add_i32 m0, s50, 0x2000
	s_add_u32 s48, s48, 0x80080
	v_lshl_add_u64 v[228:229], v[230:231], 0, s[22:23]
	s_addc_u32 s49, s49, 0
	s_add_i32 s50, s67, s58
	global_load_lds_dwordx4 v[228:229], off
	v_lshl_add_u64 v[228:229], s[48:49], 0, v[148:149]
	s_mov_b32 m0, s50
	s_nop 0
	global_load_lds_dwordx4 v[228:229], off
	v_lshl_add_u64 v[228:229], s[48:49], 0, v[152:153]
	s_add_i32 m0, s50, 0x2000
	s_nop 0
	global_load_lds_dwordx4 v[228:229], off
	v_lshl_add_u64 v[228:229], v[232:233], 0, s[22:23]
	s_mov_b32 m0, s71
	s_nop 0
	global_load_lds_dwordx4 v[228:229], off
	v_lshl_add_u64 v[228:229], v[234:235], 0, s[22:23]
	s_mov_b32 m0, s74
	s_nop 0
	global_load_lds_dwordx4 v[228:229], off
	s_waitcnt vmcnt(8)
	s_waitcnt lgkmcnt(0)
	s_barrier
	s_setprio 1
	s_waitcnt lgkmcnt(0)
	v_mfma_f32_16x16x32_bf16 v[78:81], v[58:61], v[180:183], v[78:81]
	v_mfma_f32_16x16x32_bf16 v[74:77], v[66:69], v[180:183], v[74:77]
	v_mfma_f32_16x16x32_bf16 v[54:57], v[58:61], v[188:191], v[54:57]
	v_mfma_f32_16x16x32_bf16 v[50:53], v[66:69], v[188:191], v[50:53]
	v_mfma_f32_16x16x32_bf16 v[30:33], v[58:61], v[196:199], v[30:33]
	v_mfma_f32_16x16x32_bf16 v[26:29], v[66:69], v[196:199], v[26:29]
	v_mfma_f32_16x16x32_bf16 v[14:17], v[58:61], v[204:207], v[14:17]
	v_mfma_f32_16x16x32_bf16 v[10:13], v[66:69], v[204:207], v[10:13]
	v_mfma_f32_16x16x32_bf16 v[78:81], v[62:65], v[184:187], v[78:81]
	v_mfma_f32_16x16x32_bf16 v[74:77], v[70:73], v[184:187], v[74:77]
	v_mfma_f32_16x16x32_bf16 v[54:57], v[62:65], v[192:195], v[54:57]
	v_mfma_f32_16x16x32_bf16 v[50:53], v[70:73], v[192:195], v[50:53]
	v_mfma_f32_16x16x32_bf16 v[30:33], v[62:65], v[200:203], v[30:33]
	v_mfma_f32_16x16x32_bf16 v[26:29], v[70:73], v[200:203], v[26:29]
	v_mfma_f32_16x16x32_bf16 v[14:17], v[62:65], v[224:227], v[14:17]
	v_mfma_f32_16x16x32_bf16 v[10:13], v[70:73], v[224:227], v[10:13]
	s_setprio 0
	s_setprio 1
	v_mfma_f32_16x16x32_bf16 v[42:45], v[158:161], v[180:183], v[42:45]
	v_mfma_f32_16x16x32_bf16 v[70:73], v[166:169], v[184:187], v[42:45]
	v_mfma_f32_16x16x32_bf16 v[42:45], v[172:175], v[180:183], v[46:49]
	v_mfma_f32_16x16x32_bf16 v[38:41], v[158:161], v[188:191], v[38:41]
	v_mfma_f32_16x16x32_bf16 v[34:37], v[172:175], v[188:191], v[34:37]
	v_mfma_f32_16x16x32_bf16 v[22:25], v[158:161], v[196:199], v[22:25]
	v_mfma_f32_16x16x32_bf16 v[18:21], v[172:175], v[196:199], v[18:21]
	v_mfma_f32_16x16x32_bf16 v[6:9], v[158:161], v[204:207], v[6:9]
	v_mfma_f32_16x16x32_bf16 v[2:5], v[172:175], v[204:207], v[2:5]
	v_mfma_f32_16x16x32_bf16 v[66:69], v[176:179], v[184:187], v[42:45]
	v_mfma_f32_16x16x32_bf16 v[38:41], v[166:169], v[192:195], v[38:41]
	v_mfma_f32_16x16x32_bf16 v[34:37], v[176:179], v[192:195], v[34:37]
	v_mfma_f32_16x16x32_bf16 v[22:25], v[166:169], v[200:203], v[22:25]
	v_mfma_f32_16x16x32_bf16 v[18:21], v[176:179], v[200:203], v[18:21]
	v_mfma_f32_16x16x32_bf16 v[6:9], v[166:169], v[224:227], v[6:9]
	v_mfma_f32_16x16x32_bf16 v[2:5], v[176:179], v[224:227], v[2:5]
	s_setprio 0
	s_barrier
	s_add_i32 s53, s53, 2
	s_add_u32 s35, s35, 0x100
	s_addc_u32 s52, s52, 0
	s_add_u32 s42, s42, 0x100
	s_addc_u32 s43, s43, 0
	s_cmp_gt_u32 s53, 29
	s_cbranch_scc0 .LBB0_193
	s_and_b64 vcc, exec, s[28:29]
	s_cbranch_vccz .LBB0_196
	s_barrier
